# v56 + non-temporal hint (nt) on the 64 phase-1 epilogue output stores (streamed r/k/v/z/conv planes should not displace the GEMM operands in L2/MALL)
# speedup vs baseline: 1.0043x; 1.0043x over previous
.LBB0_191:
	s_cmpk_lt_i32 s92, 0x80
	s_cselect_b64 s[0:1], -1, 0
	s_cmp_gt_i32 s52, 16
	s_cselect_b64 s[4:5], -1, 0
	s_and_b64 s[4:5], s[4:5], s[0:1]
	s_andn2_b64 vcc, exec, s[4:5]
	s_mov_b64 s[4:5], -1
	s_cbranch_vccz .LBB0_209
	s_ashr_i32 s16, s52, 2
	s_cmp_eq_u32 s16, 2
	s_mov_b32 s4, 0xfc00000
	s_cselect_b32 s4, s4, 0x13d00000
	s_cmp_lg_u32 s16, 1
	s_cselect_b32 s4, s4, 0xbb00000
	s_cmp_gt_u32 s52, 3
	s_cselect_b32 s54, s4, 0x7a00000
	s_add_u32 s34, s76, s54
	s_addc_u32 s35, s77, 0
	s_and_b64 s[0:1], s[0:1], exec
	v_readlane_b32 s56, v255, 0
	v_readlane_b32 s63, v255, 7
	v_readlane_b32 s0, v255, 37
	v_readlane_b32 s4, v255, 39
	v_readlane_b32 s5, v255, 41
	v_readlane_b32 s62, v255, 6
	s_cselect_b32 s1, s63, s0
	v_readlane_b32 s0, v255, 36
	s_cselect_b32 s39, s4, s5
	v_readlane_b32 s4, v255, 38
	v_readlane_b32 s5, v255, 40
	s_cselect_b32 s0, s62, s0
	s_cselect_b32 s38, s4, s5
	s_lshl_b32 s55, s92, 8
	s_add_i32 s55, s55, s81
	s_cmp_gt_i32 s52, 16
	s_cselect_b64 s[4:5], -1, 0
	s_cmp_eq_u32 s52, 16
	v_lshl_add_u32 v140, s52, 6, v159
	s_cselect_b64 s[12:13], -1, 0
	s_cmp_lg_u32 s52, 16
	v_lshlrev_b32_e32 v179, 1, v140
	s_cselect_b64 s[10:11], -1, 0
	v_or_b32_e32 v156, s55, v158
	s_mov_b64 s[14:15], -1
	s_and_b64 vcc, exec, s[4:5]
	v_readlane_b32 s57, v255, 1
	v_readlane_b32 s58, v255, 2
	v_readlane_b32 s59, v255, 3
	v_readlane_b32 s60, v255, 4
	v_readlane_b32 s61, v255, 5
	s_cbranch_vccz .LBB0_194
	v_mul_f32_e32 v128, 0xbfb8aa3b, v80
	v_mul_f32_e32 v129, 0xbfb8aa3b, v81
	v_mul_f32_e32 v130, 0xbfb8aa3b, v82
	v_mul_f32_e32 v131, 0xbfb8aa3b, v83
	v_exp_f32_e32 v128, v128
	v_exp_f32_e32 v129, v129
	v_exp_f32_e32 v130, v130
	v_exp_f32_e32 v131, v131
	v_add_f32_e32 v128, 1.0, v128
	v_add_f32_e32 v129, 1.0, v129
	v_add_f32_e32 v130, 1.0, v130
	v_add_f32_e32 v131, 1.0, v131
	v_rcp_f32_e32 v128, v128
	v_rcp_f32_e32 v130, v130
	v_rcp_f32_e32 v131, v131
	v_rcp_f32_e32 v129, v129
	v_pk_mul_f32 v[152:153], v[94:95], v[90:91]
	v_pk_mul_f32 v[154:155], v[92:93], v[88:89]
	v_pk_mul_f32 v[130:131], v[82:83], v[130:131]
	v_pk_mul_f32 v[128:129], v[80:81], v[128:129]
	v_pk_mul_f32 v[130:131], v[86:87], v[130:131]
	v_pk_mul_f32 v[128:129], v[84:85], v[128:129]
	v_lshl_add_u32 v157, v156, 11, v179
	v_cvt_pk_f16_f32 v153, v152, v153
	v_cvt_pk_f16_f32 v152, v154, v155
	v_cvt_pk_f16_f32 v131, v130, v131
	v_cvt_pk_f16_f32 v130, v128, v129
	global_store_dwordx2 v157, v[152:153], s[0:1] nt
	global_store_dwordx2 v157, v[130:131], s[38:39] nt
	s_mov_b64 s[14:15], 0
.LBB0_194:
	s_lshl_b32 s17, s52, 8
	v_cndmask_b32_e64 v128, 0, 1, s[10:11]
	s_and_b32 s53, s17, 0x300
	s_andn2_b64 vcc, exec, s[14:15]
	v_cmp_ne_u32_e64 s[10:11], 1, v128
	s_cbranch_vccnz .LBB0_197
	v_lshlrev_b32_e32 v128, 10, v156
	s_and_b64 s[14:15], s[12:13], exec
	v_or3_b32 v128, v128, s53, v142
	s_cselect_b32 s14, 0x17e00000, s54
	v_lshl_or_b32 v129, v156, 8, v160
	v_lshlrev_b32_e32 v128, 1, v128
	s_cselect_b32 s15, 0, 0
	s_add_u32 s14, s76, s14
	v_cvt_pk_f16_f32 v155, v94, v95
	v_cvt_pk_f16_f32 v154, v92, v93
	v_cvt_pk_f16_f32 v153, v86, v87
	v_cvt_pk_f16_f32 v152, v84, v85
	v_cndmask_b32_e64 v129, v128, v129, s[12:13]
	s_addc_u32 s15, s77, s15
	s_and_b64 vcc, exec, s[10:11]
	global_store_dwordx4 v129, v[152:155], s[14:15] nt
	s_cbranch_vccnz .LBB0_197
	s_nop 0
	v_cvt_pk_f16_f32 v155, v82, v83
	v_cvt_pk_f16_f32 v154, v80, v81
	v_cvt_pk_f16_f32 v153, v90, v91
	v_cvt_pk_f16_f32 v152, v88, v89
	global_store_dwordx4 v128, v[152:155], s[34:35] offset:256 nt
.LBB0_197:
	v_cndmask_b32_e64 v129, 0, 1, s[4:5]
	v_or_b32_e32 v128, 1, v156
	v_cmp_ne_u32_e64 s[14:15], 1, v129
	s_andn2_b64 vcc, exec, s[4:5]
	s_mov_b64 s[4:5], -1
	s_cbranch_vccnz .LBB0_199
	v_mul_f32_e32 v129, 0xbfb8aa3b, v64
	v_exp_f32_e32 v129, v129
	v_mul_f32_e32 v130, 0xbfb8aa3b, v65
	v_mul_f32_e32 v131, 0xbfb8aa3b, v66
	v_exp_f32_e32 v152, v130
	v_add_f32_e32 v129, 1.0, v129
	v_rcp_f32_e32 v130, v129
	v_exp_f32_e32 v129, v131
	v_mul_f32_e32 v131, 0xbfb8aa3b, v67
	v_exp_f32_e32 v131, v131
	v_add_f32_e32 v154, 1.0, v152
	v_add_f32_e32 v129, 1.0, v129
	v_rcp_f32_e32 v152, v129
	v_add_f32_e32 v129, 1.0, v131
	v_rcp_f32_e32 v153, v129
	v_rcp_f32_e32 v131, v154
	v_pk_mul_f32 v[154:155], v[78:79], v[74:75]
	v_pk_mul_f32 v[180:181], v[76:77], v[72:73]
	v_pk_mul_f32 v[152:153], v[66:67], v[152:153]
	v_pk_mul_f32 v[130:131], v[64:65], v[130:131]
	v_pk_mul_f32 v[152:153], v[70:71], v[152:153]
	v_pk_mul_f32 v[130:131], v[68:69], v[130:131]
	v_lshl_add_u32 v129, v128, 11, v179
	v_cvt_pk_f16_f32 v155, v154, v155
	v_cvt_pk_f16_f32 v154, v180, v181
	v_cvt_pk_f16_f32 v153, v152, v153
	v_cvt_pk_f16_f32 v152, v130, v131
	s_mov_b64 s[4:5], 0
	global_store_dwordx2 v129, v[154:155], s[0:1] nt
	global_store_dwordx2 v129, v[152:153], s[38:39] nt
.LBB0_199:
	s_andn2_b64 vcc, exec, s[4:5]
	s_cbranch_vccnz .LBB0_202
	v_lshlrev_b32_e32 v129, 10, v128
	s_and_b64 s[4:5], s[12:13], exec
	v_lshl_or_b32 v130, v128, 8, v160
	v_or3_b32 v128, v129, s53, v142
	s_cselect_b32 s4, 0x17e00000, s54
	v_lshlrev_b32_e32 v128, 1, v128
	s_cselect_b32 s5, 0, 0
	s_add_u32 s4, s76, s4
	v_cvt_pk_f16_f32 v155, v78, v79
	v_cvt_pk_f16_f32 v154, v76, v77
	v_cvt_pk_f16_f32 v153, v70, v71
	v_cvt_pk_f16_f32 v152, v68, v69
	v_cndmask_b32_e64 v129, v128, v130, s[12:13]
	s_addc_u32 s5, s77, s5
	s_and_b64 vcc, exec, s[10:11]
	global_store_dwordx4 v129, v[152:155], s[4:5] nt
	s_cbranch_vccnz .LBB0_202
	s_nop 0
	v_cvt_pk_f16_f32 v155, v66, v67
	v_cvt_pk_f16_f32 v154, v64, v65
	v_cvt_pk_f16_f32 v153, v74, v75
	v_cvt_pk_f16_f32 v152, v72, v73
	global_store_dwordx4 v128, v[152:155], s[34:35] offset:256 nt

.LBB0_206:
	v_mul_f32_e32 v128, 0xbfb8aa3b, v48
	v_mul_f32_e32 v129, 0xbfb8aa3b, v49
	v_mul_f32_e32 v130, 0xbfb8aa3b, v50
	v_mul_f32_e32 v131, 0xbfb8aa3b, v51
	v_exp_f32_e32 v128, v128
	v_exp_f32_e32 v129, v129
	v_exp_f32_e32 v130, v130
	v_exp_f32_e32 v131, v131
	v_add_f32_e32 v128, 1.0, v128
	v_add_f32_e32 v129, 1.0, v129
	v_add_f32_e32 v130, 1.0, v130
	v_add_f32_e32 v131, 1.0, v131
	v_rcp_f32_e32 v128, v128
	v_rcp_f32_e32 v130, v130
	v_rcp_f32_e32 v131, v131
	v_rcp_f32_e32 v129, v129
	v_lshl_add_u32 v181, v180, 11, v179
	v_cmp_lt_i32_e32 vcc, -1, v153
	v_pk_mul_f32 v[130:131], v[50:51], v[130:131]
	v_pk_mul_f32 v[128:129], v[48:49], v[128:129]
	v_pk_mul_f32 v[184:185], v[54:55], v[130:131]
	v_pk_mul_f32 v[182:183], v[52:53], v[128:129]
	v_pk_mul_f32 v[130:131], v[126:127], v[122:123]
	v_pk_mul_f32 v[128:129], v[124:125], v[120:121]
	v_cvt_pk_f16_f32 v187, v130, v131
	v_cvt_pk_f16_f32 v186, v128, v129
	v_cvt_pk_f16_f32 v185, v184, v185
	v_cvt_pk_f16_f32 v184, v182, v183
	global_store_dwordx2 v181, v[186:187], s[0:1] nt
	global_store_dwordx2 v181, v[184:185], s[38:39] nt
	s_and_saveexec_b64 s[4:5], vcc
	s_cbranch_execz .LBB0_208
	v_readlane_b32 s56, v255, 0
	v_readlane_b32 s62, v255, 6
	v_readlane_b32 s63, v255, 7
	v_ashrrev_i32_e32 v153, 31, v152
	v_lshlrev_b64 v[152:153], 13, v[152:153]
	v_lshl_add_u64 v[154:155], v[154:155], 2, s[62:63]
	v_lshl_add_u64 v[152:153], v[154:155], 0, v[152:153]
	v_lshl_add_u64 v[152:153], v[140:141], 2, v[152:153]
	v_readlane_b32 s57, v255, 1
	v_readlane_b32 s58, v255, 2
	v_readlane_b32 s59, v255, 3
	v_readlane_b32 s60, v255, 4
	v_readlane_b32 s61, v255, 5
	global_store_dwordx4 v[152:153], v[128:131], off nt

.LBB0_209:
	s_and_b64 vcc, exec, s[4:5]
	s_cbranch_vccz .LBB0_302
	s_lshl_b32 s4, s92, 8
	s_add_i32 s4, s4, s81
	s_and_b32 s0, s4, 0xfc0
	v_or_b32_e32 v128, s0, v158
	s_movk_i32 s0, 0xffc
	v_lshl_add_u32 v140, s52, 6, v159
	v_pk_mul_f32 v[122:123], v[126:127], v[122:123]
	v_pk_mul_f32 v[120:121], v[124:125], v[120:121]
	v_cmp_eq_u32_e32 vcc, s0, v128
	s_and_saveexec_b64 s[0:1], vcc
	s_cbranch_execz .LBB0_212
	s_ashr_i32 s10, s4, 12
	s_ashr_i32 s11, s10, 31
	s_lshl_b64 s[10:11], s[10:11], 13
	v_readlane_b32 s5, v255, 44
	s_add_u32 s10, s5, s10
	v_readlane_b32 s5, v255, 45
	s_addc_u32 s11, s5, s11
	v_lshl_add_u64 v[124:125], v[140:141], 2, s[10:11]
	global_store_dwordx4 v[124:125], v[120:123], off nt
.LBB0_212:
	s_or_b64 exec, exec, s[0:1]
	s_movk_i32 s0, 0xffa
	v_pk_mul_f32 v[118:119], v[118:119], v[114:115]
	v_pk_mul_f32 v[116:117], v[116:117], v[112:113]
	v_cmp_lt_u32_e32 vcc, s0, v128
	s_and_saveexec_b64 s[0:1], vcc
	s_cbranch_execz .LBB0_214
	s_ashr_i32 s10, s4, 12
	s_ashr_i32 s11, s10, 31
	s_lshl_b64 s[10:11], s[10:11], 13
	v_readlane_b32 s5, v255, 44
	v_add_u32_e32 v112, 0xfffff005, v128
	v_mov_b32_e32 v113, v141
	s_add_u32 s10, s5, s10
	v_readlane_b32 s5, v255, 45
	s_addc_u32 s11, s5, s11
	v_lshlrev_b64 v[112:113], 12, v[112:113]
	v_lshl_add_u64 v[112:113], s[10:11], 0, v[112:113]
	v_lshl_add_u64 v[112:113], v[140:141], 2, v[112:113]
	global_store_dwordx4 v[112:113], v[116:119], off nt
.LBB0_214:
	s_or_b64 exec, exec, s[0:1]
	s_addk_i32 s4, 0x80
	s_and_b32 s0, s4, 0xfc0
	v_or_b32_e32 v112, s0, v158
	s_movk_i32 s0, 0xffc
	v_pk_mul_f32 v[106:107], v[110:111], v[106:107]
	v_pk_mul_f32 v[104:105], v[108:109], v[104:105]
	v_cmp_eq_u32_e32 vcc, s0, v112
	s_and_saveexec_b64 s[0:1], vcc
	s_cbranch_execz .LBB0_216
	s_ashr_i32 s10, s4, 12
	s_ashr_i32 s11, s10, 31
	s_lshl_b64 s[10:11], s[10:11], 13
	v_readlane_b32 s5, v255, 44
	s_add_u32 s10, s5, s10
	v_readlane_b32 s5, v255, 45
	s_addc_u32 s11, s5, s11
	v_lshl_add_u64 v[108:109], v[140:141], 2, s[10:11]
	global_store_dwordx4 v[108:109], v[104:107], off nt
.LBB0_216:
	s_or_b64 exec, exec, s[0:1]
	s_movk_i32 s0, 0xffa
	v_pk_mul_f32 v[98:99], v[102:103], v[98:99]
	v_pk_mul_f32 v[96:97], v[100:101], v[96:97]
	v_cmp_lt_u32_e32 vcc, s0, v112
	s_and_saveexec_b64 s[0:1], vcc
	s_cbranch_execz .LBB0_218
	s_ashr_i32 s4, s4, 12
	s_ashr_i32 s5, s4, 31
	s_lshl_b64 s[4:5], s[4:5], 13
	v_readlane_b32 s10, v255, 44
	v_add_u32_e32 v100, 0xfffff005, v112
	v_mov_b32_e32 v101, v141
	s_add_u32 s4, s10, s4
	v_readlane_b32 s10, v255, 45
	s_addc_u32 s5, s10, s5
	v_lshlrev_b64 v[100:101], 12, v[100:101]
	v_lshl_add_u64 v[100:101], s[4:5], 0, v[100:101]
	v_lshl_add_u64 v[100:101], v[140:141], 2, v[100:101]
	global_store_dwordx4 v[100:101], v[96:99], off nt
.LBB0_218:
	s_or_b64 exec, exec, s[0:1]
	s_mov_b64 s[0:1], exec
	v_readlane_b32 s4, v255, 56
	v_readlane_b32 s5, v255, 57
	s_and_b64 s[4:5], s[0:1], s[4:5]
	s_mov_b64 exec, s[4:5]
	s_cbranch_execz .LBB0_221
	s_and_b64 vcc, exec, s[70:71]
	ds_write_b128 v165, v[120:123]
	ds_write_b128 v165, v[116:119] offset:256
	ds_write_b128 v165, v[104:107] offset:1024
	ds_write_b128 v165, v[96:99] offset:1280
	s_cbranch_vccz .LBB0_221
	s_ashr_i32 s93, s92, 31
	s_lshl_b64 s[4:5], s[92:93], 13
	v_readlane_b32 s10, v255, 46
	s_add_u32 s4, s10, s4
	v_readlane_b32 s10, v255, 47
	s_addc_u32 s5, s10, s5
	v_lshl_add_u64 v[100:101], v[140:141], 2, s[4:5]
	global_store_dwordx4 v[100:101], v[104:107], off nt
	v_add_co_u32_e32 v100, vcc, 0x1000, v100
	s_nop 1
	v_addc_co_u32_e32 v101, vcc, 0, v101, vcc
	global_store_dwordx4 v[100:101], v[96:99], off nt

.LBB0_223:
	s_or_b64 exec, exec, s[0:1]
	v_pk_mul_f32 v[90:91], v[94:95], v[90:91]
	v_pk_mul_f32 v[88:89], v[92:93], v[88:89]
	v_mul_f32_e32 v92, 0xbfb8aa3b, v80
	v_mul_f32_e32 v93, 0xbfb8aa3b, v81
	v_mul_f32_e32 v94, 0xbfb8aa3b, v82
	v_mul_f32_e32 v95, 0xbfb8aa3b, v83
	v_exp_f32_e32 v92, v92
	v_exp_f32_e32 v93, v93
	v_exp_f32_e32 v94, v94
	v_exp_f32_e32 v95, v95
	v_add_f32_e32 v92, 1.0, v92
	v_add_f32_e32 v93, 1.0, v93
	v_add_f32_e32 v94, 1.0, v94
	v_add_f32_e32 v95, 1.0, v95
	v_rcp_f32_e32 v92, v92
	v_rcp_f32_e32 v93, v93
	v_rcp_f32_e32 v94, v94
	v_rcp_f32_e32 v95, v95
	s_and_b32 s0, s92, 15
	v_pk_mul_f32 v[80:81], v[80:81], v[92:93]
	s_cmp_lg_u32 s0, 0
	v_pk_mul_f32 v[82:83], v[82:83], v[94:95]
	v_pk_mul_f32 v[80:81], v[84:85], v[80:81]
	v_pk_mul_f32 v[82:83], v[86:87], v[82:83]
	s_waitcnt vmcnt(0) lgkmcnt(0)
	v_pk_mul_f32 v[84:85], v[110:111], v[126:127]
	v_pk_mul_f32 v[86:87], v[108:109], v[124:125]
	v_pk_fma_f32 v[84:85], v[90:91], v[114:115], v[84:85]
	v_pk_fma_f32 v[92:93], v[88:89], v[112:113], v[86:87]
	v_readlane_b32 s4, v255, 62
	s_cselect_b64 s[0:1], -1, 0
	v_pk_fma_f32 v[86:87], v[102:103], v[130:131], v[84:85]
	v_pk_fma_f32 v[84:85], v[100:101], v[128:129], v[92:93]
	v_readlane_b32 s5, v255, 63
	s_and_b64 s[0:1], s[4:5], s[0:1]
	v_pk_mul_f32 v[84:85], v[80:81], v[84:85]
	s_and_saveexec_b64 s[4:5], s[0:1]
	s_xor_b64 s[4:5], exec, s[4:5]
	s_cbranch_execz .LBB0_225
	s_ashr_i32 s93, s92, 31
	s_lshl_b64 s[10:11], s[92:93], 13
	v_readlane_b32 s12, v255, 52
	s_add_u32 s12, s12, s10
	v_readlane_b32 s13, v255, 53
	s_addc_u32 s13, s13, s11
	v_pk_mul_f32 v[86:87], v[82:83], v[86:87]
	v_lshl_add_u64 v[92:93], s[12:13], 0, v[152:153]
	v_readlane_b32 s12, v255, 54
	s_add_u32 s10, s12, s10
	v_readlane_b32 s12, v255, 55
	s_addc_u32 s11, s12, s11
	v_lshl_add_u64 v[94:95], s[10:11], 0, v[152:153]
	global_store_dwordx4 v[92:93], v[84:87], off nt
	global_store_dwordx4 v[94:95], v[80:83], off nt
.LBB0_225:
	s_or_saveexec_b64 s[4:5], s[4:5]
	s_nop 0
	v_lshlrev_b32_e32 v80, 1, v140
	s_xor_b64 exec, exec, s[4:5]
	s_cbranch_execz .LBB0_227
	v_pk_mul_f32 v[82:83], v[82:83], v[86:87]
	s_lshl_b32 s10, s92, 19
	v_cvt_pk_f16_f32 v83, v82, v83
	v_cvt_pk_f16_f32 v82, v84, v85
	v_add3_u32 v81, s10, v163, v80
	global_store_dwordx2 v81, v[82:83], s[84:85] nt
.LBB0_227:
	s_or_b64 exec, exec, s[4:5]
	v_pk_mul_f32 v[74:75], v[78:79], v[74:75]
	v_pk_mul_f32 v[72:73], v[76:77], v[72:73]
	v_mul_f32_e32 v76, 0xbfb8aa3b, v64
	v_mul_f32_e32 v77, 0xbfb8aa3b, v65
	v_mul_f32_e32 v78, 0xbfb8aa3b, v66
	v_mul_f32_e32 v79, 0xbfb8aa3b, v67
	v_exp_f32_e32 v76, v76
	v_exp_f32_e32 v77, v77
	v_exp_f32_e32 v78, v78
	v_exp_f32_e32 v79, v79
	v_add_f32_e32 v76, 1.0, v76
	v_add_f32_e32 v77, 1.0, v77
	v_add_f32_e32 v78, 1.0, v78
	v_add_f32_e32 v79, 1.0, v79
	v_rcp_f32_e32 v76, v76
	v_rcp_f32_e32 v77, v77
	v_rcp_f32_e32 v78, v78
	v_rcp_f32_e32 v79, v79
	v_pk_mul_f32 v[64:65], v[64:65], v[76:77]
	s_nop 0
	v_pk_mul_f32 v[64:65], v[68:69], v[64:65]
	v_pk_mul_f32 v[66:67], v[66:67], v[78:79]
	v_pk_mul_f32 v[68:69], v[74:75], v[114:115]
	v_pk_mul_f32 v[66:67], v[70:71], v[66:67]
	v_pk_mul_f32 v[70:71], v[72:73], v[112:113]
	v_pk_fma_f32 v[68:69], v[90:91], v[110:111], v[68:69]
	v_pk_fma_f32 v[76:77], v[88:89], v[108:109], v[70:71]
	v_pk_fma_f32 v[70:71], v[102:103], v[126:127], v[68:69]
	v_pk_fma_f32 v[68:69], v[100:101], v[124:125], v[76:77]
	s_nop 0
	v_pk_mul_f32 v[68:69], v[64:65], v[68:69]
	s_and_saveexec_b64 s[10:11], s[0:1]
	s_xor_b64 s[0:1], exec, s[10:11]
	s_cbranch_execz .LBB0_229
	s_ashr_i32 s93, s92, 31
	s_lshl_b64 s[4:5], s[92:93], 13
	s_add_u32 s4, s76, s4
	s_addc_u32 s5, s77, s5
	v_lshl_add_u64 v[76:77], v[140:141], 2, s[4:5]
	v_add_co_u32_e32 v78, vcc, 0x1c901000, v76
	v_pk_mul_f32 v[70:71], v[66:67], v[70:71]
	s_nop 0
	v_addc_co_u32_e32 v79, vcc, 0, v77, vcc
	global_store_dwordx4 v[78:79], v[68:71], off nt
	s_lshl_b32 s4, s92, 19
	s_nop 0
	v_add_co_u32_e32 v68, vcc, 0x1ca01000, v76
	s_nop 1
	v_addc_co_u32_e32 v69, vcc, 0, v77, vcc
	global_store_dwordx4 v[68:69], v[64:67], off nt
.LBB0_229:
	s_or_saveexec_b64 s[0:1], s[0:1]
	s_nop 0
	v_mov_b32_e32 v64, 0
	v_mov_b32_e32 v65, s4
	s_xor_b64 exec, exec, s[0:1]
	s_cbranch_execz .LBB0_231
	v_pk_mul_f32 v[64:65], v[66:67], v[70:71]
	s_lshl_b32 s4, s92, 19
	v_cvt_pk_f16_f32 v65, v64, v65
	v_cvt_pk_f16_f32 v64, v68, v69
	v_add3_u32 v66, v164, s4, v80
	global_store_dwordx2 v66, v[64:65], s[84:85] nt
	v_mov_b32_e32 v65, s4
	v_mov_b32_e32 v64, v163
.LBB0_231:
	s_or_b64 exec, exec, s[0:1]
	v_mul_f32_e32 v66, 0xbfb8aa3b, v56
	v_mul_f32_e32 v67, 0xbfb8aa3b, v57
	v_mul_f32_e32 v68, 0xbfb8aa3b, v58
	v_mul_f32_e32 v69, 0xbfb8aa3b, v59
	v_exp_f32_e32 v66, v66
	v_exp_f32_e32 v67, v67
	v_exp_f32_e32 v68, v68
	v_exp_f32_e32 v69, v69
	v_add_f32_e32 v66, 1.0, v66
	v_add_f32_e32 v67, 1.0, v67
	v_add_f32_e32 v68, 1.0, v68
	v_add_f32_e32 v69, 1.0, v69
	v_rcp_f32_e32 v66, v66
	v_rcp_f32_e32 v67, v67
	v_rcp_f32_e32 v68, v68
	v_rcp_f32_e32 v69, v69
	v_pk_mul_f32 v[56:57], v[56:57], v[66:67]
	s_nop 0
	v_pk_mul_f32 v[60:61], v[60:61], v[56:57]
	v_pk_mul_f32 v[58:59], v[58:59], v[68:69]
	v_mul_f32_e32 v56, 0xbfb8aa3b, v48
	v_pk_mul_f32 v[58:59], v[62:63], v[58:59]
	v_mul_f32_e32 v57, 0xbfb8aa3b, v49
	v_mul_f32_e32 v62, 0xbfb8aa3b, v50
	v_mul_f32_e32 v63, 0xbfb8aa3b, v51
	v_exp_f32_e32 v56, v56
	v_exp_f32_e32 v57, v57
	v_exp_f32_e32 v62, v62
	v_exp_f32_e32 v63, v63
	v_add_f32_e32 v56, 1.0, v56
	v_add_f32_e32 v57, 1.0, v57
	v_add_f32_e32 v62, 1.0, v62
	v_add_f32_e32 v63, 1.0, v63
	v_rcp_f32_e32 v56, v56
	v_rcp_f32_e32 v57, v57
	v_rcp_f32_e32 v62, v62
	v_rcp_f32_e32 v63, v63
	v_pk_mul_f32 v[48:49], v[48:49], v[56:57]
	s_nop 0
	v_pk_mul_f32 v[48:49], v[52:53], v[48:49]
	v_pk_mul_f32 v[50:51], v[50:51], v[62:63]
	v_pk_mul_f32 v[52:53], v[122:123], v[114:115]
	v_pk_mul_f32 v[50:51], v[54:55], v[50:51]
	v_pk_mul_f32 v[54:55], v[120:121], v[112:113]
	v_pk_fma_f32 v[52:53], v[74:75], v[110:111], v[52:53]
	v_pk_fma_f32 v[54:55], v[72:73], v[108:109], v[54:55]
	v_pk_fma_f32 v[52:53], v[90:91], v[102:103], v[52:53]
	v_pk_fma_f32 v[54:55], v[88:89], v[100:101], v[54:55]
	v_pk_mul_f32 v[50:51], v[50:51], v[52:53]
	v_pk_mul_f32 v[48:49], v[48:49], v[54:55]
	v_cvt_pk_f16_f32 v51, v50, v51
	v_cvt_pk_f16_f32 v50, v48, v49
	v_add_u32_e32 v48, v65, v64
	v_add_u32_e32 v56, v80, v48
	v_add_u32_e32 v48, 0x1000, v56
	global_store_dwordx2 v48, v[50:51], s[84:85] nt
	v_pk_mul_f32 v[48:49], v[118:119], v[114:115]
	v_pk_mul_f32 v[50:51], v[116:117], v[112:113]
	v_pk_fma_f32 v[48:49], v[122:123], v[110:111], v[48:49]
	v_pk_fma_f32 v[50:51], v[120:121], v[108:109], v[50:51]
	v_pk_fma_f32 v[48:49], v[74:75], v[102:103], v[48:49]
	v_pk_fma_f32 v[50:51], v[72:73], v[100:101], v[50:51]
	v_pk_mul_f32 v[48:49], v[58:59], v[48:49]
	v_pk_mul_f32 v[50:51], v[60:61], v[50:51]
	v_cvt_pk_f16_f32 v49, v48, v49
	v_cvt_pk_f16_f32 v48, v50, v51
	v_add_u32_e32 v50, 0x1800, v56
	global_store_dwordx2 v50, v[48:49], s[84:85] nt
	v_mov_b32_dpp v48, v96 row_shr:1 row_mask:0xf bank_mask:0xf bound_ctrl:1
	v_mov_b32_dpp v52, v104 row_shr:1 row_mask:0xf bank_mask:0xf bound_ctrl:1
	v_mov_b32_dpp v49, v97 row_shr:1 row_mask:0xf bank_mask:0xf bound_ctrl:1
	v_mov_b32_dpp v53, v105 row_shr:1 row_mask:0xf bank_mask:0xf bound_ctrl:1
	v_mov_b32_dpp v50, v98 row_shr:1 row_mask:0xf bank_mask:0xf bound_ctrl:1
	v_mov_b32_dpp v54, v106 row_shr:1 row_mask:0xf bank_mask:0xf bound_ctrl:1
	v_mov_b32_dpp v51, v99 row_shr:1 row_mask:0xf bank_mask:0xf bound_ctrl:1
	v_mov_b32_dpp v55, v107 row_shr:1 row_mask:0xf bank_mask:0xf bound_ctrl:1
	s_mov_b64 s[0:1], exec
	v_readlane_b32 s4, v255, 58
	v_readlane_b32 s5, v255, 59
	s_and_b64 s[4:5], s[0:1], s[4:5]
	s_mov_b64 exec, s[4:5]
	s_cbranch_execz .LBB0_233
	ds_read_b128 v[52:55], v165 offset:512
	ds_read_b128 v[48:51], v165 offset:768
.LBB0_233:
	s_or_b64 exec, exec, s[0:1]
	v_pk_mul_f32 v[26:27], v[34:35], v[26:27]
	v_pk_mul_f32 v[24:25], v[32:33], v[24:25]
	v_mul_f32_e32 v32, 0xbfb8aa3b, v16
	v_mul_f32_e32 v33, 0xbfb8aa3b, v17
	v_mul_f32_e32 v34, 0xbfb8aa3b, v18
	v_mul_f32_e32 v35, 0xbfb8aa3b, v19
	v_exp_f32_e32 v32, v32
	v_exp_f32_e32 v33, v33
	v_exp_f32_e32 v34, v34
	v_exp_f32_e32 v35, v35
	v_pk_mul_f32 v[42:43], v[46:47], v[42:43]
	v_pk_mul_f32 v[40:41], v[44:45], v[40:41]
	v_mul_f32_e32 v44, 0xbfb8aa3b, v28
	v_mul_f32_e32 v45, 0xbfb8aa3b, v29
	v_mul_f32_e32 v46, 0xbfb8aa3b, v30
	v_mul_f32_e32 v47, 0xbfb8aa3b, v31
	v_exp_f32_e32 v44, v44
	v_exp_f32_e32 v45, v45
	v_exp_f32_e32 v46, v46
	v_exp_f32_e32 v47, v47
	v_add_f32_e32 v32, 1.0, v32
	v_add_f32_e32 v33, 1.0, v33
	v_add_f32_e32 v34, 1.0, v34
	v_add_f32_e32 v35, 1.0, v35
	v_rcp_f32_e32 v32, v32
	v_rcp_f32_e32 v33, v33
	v_rcp_f32_e32 v34, v34
	v_rcp_f32_e32 v35, v35
	v_add_f32_e32 v44, 1.0, v44
	v_add_f32_e32 v45, 1.0, v45
	v_add_f32_e32 v46, 1.0, v46
	v_add_f32_e32 v47, 1.0, v47
	v_rcp_f32_e32 v44, v44
	v_rcp_f32_e32 v45, v45
	v_rcp_f32_e32 v46, v46
	v_rcp_f32_e32 v47, v47
	v_pk_mul_f32 v[16:17], v[16:17], v[32:33]
	v_pk_mul_f32 v[18:19], v[18:19], v[34:35]
	v_pk_mul_f32 v[16:17], v[20:21], v[16:17]
	v_pk_mul_f32 v[18:19], v[22:23], v[18:19]
	s_waitcnt lgkmcnt(0)
	v_pk_mul_f32 v[20:21], v[110:111], v[50:51]
	v_pk_mul_f32 v[22:23], v[108:109], v[48:49]
	v_pk_mul_f32 v[28:29], v[28:29], v[44:45]
	v_pk_mul_f32 v[30:31], v[30:31], v[46:47]
	v_pk_fma_f32 v[20:21], v[42:43], v[114:115], v[20:21]
	v_pk_fma_f32 v[22:23], v[40:41], v[112:113], v[22:23]
	v_pk_mul_f32 v[30:31], v[38:39], v[30:31]
	v_pk_mul_f32 v[28:29], v[36:37], v[28:29]
	v_pk_fma_f32 v[20:21], v[102:103], v[54:55], v[20:21]
	v_pk_fma_f32 v[22:23], v[100:101], v[52:53], v[22:23]
	v_pk_mul_f32 v[20:21], v[30:31], v[20:21]
	v_pk_mul_f32 v[22:23], v[28:29], v[22:23]
	v_cvt_pk_f16_f32 v21, v20, v21
	v_cvt_pk_f16_f32 v20, v22, v23
	v_add_u32_e32 v22, 0x40000, v56
	global_store_dwordx2 v22, v[20:21], s[84:85] nt
	v_pk_mul_f32 v[20:21], v[26:27], v[114:115]
	v_pk_mul_f32 v[22:23], v[24:25], v[112:113]
	v_pk_fma_f32 v[20:21], v[42:43], v[110:111], v[20:21]
	v_pk_fma_f32 v[22:23], v[40:41], v[108:109], v[22:23]
	v_pk_fma_f32 v[20:21], v[102:103], v[50:51], v[20:21]
	v_pk_fma_f32 v[22:23], v[100:101], v[48:49], v[22:23]
	v_pk_mul_f32 v[18:19], v[18:19], v[20:21]
	v_pk_mul_f32 v[16:17], v[16:17], v[22:23]
	v_cvt_pk_f16_f32 v19, v18, v19
	v_cvt_pk_f16_f32 v18, v16, v17
	v_add_u32_e32 v16, 0x40800, v56
	global_store_dwordx2 v16, v[18:19], s[84:85] nt
	v_mul_f32_e32 v16, 0xbfb8aa3b, v8
	v_mul_f32_e32 v17, 0xbfb8aa3b, v9
	v_mul_f32_e32 v18, 0xbfb8aa3b, v10
	v_mul_f32_e32 v19, 0xbfb8aa3b, v11
	v_exp_f32_e32 v16, v16
	v_exp_f32_e32 v17, v17
	v_exp_f32_e32 v18, v18
	v_exp_f32_e32 v19, v19
	v_add_f32_e32 v16, 1.0, v16
	v_add_f32_e32 v17, 1.0, v17
	v_add_f32_e32 v18, 1.0, v18
	v_add_f32_e32 v19, 1.0, v19
	v_rcp_f32_e32 v16, v16
	v_rcp_f32_e32 v17, v17
	v_rcp_f32_e32 v18, v18
	v_rcp_f32_e32 v19, v19
	v_pk_mul_f32 v[8:9], v[8:9], v[16:17]
	s_nop 0
	v_pk_mul_f32 v[8:9], v[12:13], v[8:9]
	v_pk_mul_f32 v[10:11], v[10:11], v[18:19]
	v_mul_f32_e32 v12, 0xbfb8aa3b, v0
	v_pk_mul_f32 v[10:11], v[14:15], v[10:11]
	v_mul_f32_e32 v13, 0xbfb8aa3b, v1
	v_mul_f32_e32 v14, 0xbfb8aa3b, v2
	v_mul_f32_e32 v15, 0xbfb8aa3b, v3
	v_exp_f32_e32 v12, v12
	v_exp_f32_e32 v13, v13
	v_exp_f32_e32 v14, v14
	v_exp_f32_e32 v15, v15
	v_add_f32_e32 v12, 1.0, v12
	v_add_f32_e32 v13, 1.0, v13
	v_add_f32_e32 v14, 1.0, v14
	v_add_f32_e32 v15, 1.0, v15
	v_rcp_f32_e32 v12, v12
	v_rcp_f32_e32 v13, v13
	v_rcp_f32_e32 v14, v14
	v_rcp_f32_e32 v15, v15
	v_pk_mul_f32 v[0:1], v[0:1], v[12:13]
	s_nop 0
	v_pk_mul_f32 v[0:1], v[4:5], v[0:1]
	v_pk_mul_f32 v[2:3], v[2:3], v[14:15]
	v_pk_mul_f32 v[4:5], v[106:107], v[114:115]
	v_pk_mul_f32 v[2:3], v[6:7], v[2:3]
	v_pk_mul_f32 v[6:7], v[104:105], v[112:113]
	v_pk_fma_f32 v[4:5], v[26:27], v[110:111], v[4:5]
	v_pk_fma_f32 v[6:7], v[24:25], v[108:109], v[6:7]
	v_pk_fma_f32 v[4:5], v[42:43], v[102:103], v[4:5]
	v_pk_fma_f32 v[6:7], v[40:41], v[100:101], v[6:7]
	v_pk_mul_f32 v[2:3], v[2:3], v[4:5]
	v_pk_mul_f32 v[0:1], v[0:1], v[6:7]
	v_cvt_pk_f16_f32 v3, v2, v3
	v_cvt_pk_f16_f32 v2, v0, v1
	v_add_u32_e32 v0, 0x41000, v56
	global_store_dwordx2 v0, v[2:3], s[84:85] nt
	v_pk_mul_f32 v[0:1], v[98:99], v[114:115]
	v_pk_mul_f32 v[2:3], v[96:97], v[112:113]
	v_pk_fma_f32 v[0:1], v[106:107], v[110:111], v[0:1]
	v_pk_fma_f32 v[2:3], v[104:105], v[108:109], v[2:3]
	v_pk_fma_f32 v[0:1], v[26:27], v[102:103], v[0:1]
	v_pk_fma_f32 v[2:3], v[24:25], v[100:101], v[2:3]
	v_pk_mul_f32 v[0:1], v[10:11], v[0:1]
	v_pk_mul_f32 v[2:3], v[8:9], v[2:3]
	v_cvt_pk_f16_f32 v1, v0, v1
	v_cvt_pk_f16_f32 v0, v2, v3
	v_add_u32_e32 v2, 0x41800, v56
	global_store_dwordx2 v2, v[0:1], s[84:85] nt
	s_andn2_b64 vcc, exec, s[8:9]
	s_mov_b64 s[0:1], -1
	s_cbranch_vccnz .LBB0_180
	s_branch .LBB0_303

.LBB0_237:
	v_lshlrev_b32_e32 v128, 10, v180
	s_and_b64 s[4:5], s[12:13], exec
	v_or3_b32 v128, v128, s53, v142
	s_cselect_b32 s4, 0x17e00000, s54
	v_lshl_or_b32 v129, v180, 8, v160
	v_lshlrev_b32_e32 v128, 1, v128
	s_cselect_b32 s5, 0, 0
	s_add_u32 s4, s76, s4
	v_cvt_pk_f16_f32 v155, v126, v127
	v_cvt_pk_f16_f32 v154, v124, v125
	v_cvt_pk_f16_f32 v153, v54, v55
	v_cvt_pk_f16_f32 v152, v52, v53
	v_cndmask_b32_e64 v129, v128, v129, s[12:13]
	s_addc_u32 s5, s77, s5
	s_and_b64 vcc, exec, s[10:11]
	global_store_dwordx4 v129, v[152:155], s[4:5] nt
	s_cbranch_vccnz .LBB0_239
	s_nop 0
	v_cvt_pk_f16_f32 v155, v50, v51
	v_cvt_pk_f16_f32 v154, v48, v49
	v_cvt_pk_f16_f32 v153, v122, v123
	v_cvt_pk_f16_f32 v152, v120, v121
	global_store_dwordx4 v128, v[152:155], s[34:35] offset:256 nt

.LBB0_244:
	s_or_b64 exec, exec, s[4:5]
	s_lshl_b32 s4, s16, 10
	s_cmp_lg_u32 s16, 3
	s_cselect_b32 s16, s4, 0xc80
	s_and_b64 vcc, exec, s[14:15]
	s_mov_b64 s[4:5], -1
	s_cbranch_vccnz .LBB0_248
	v_mul_f32_e32 v128, 0xbfb8aa3b, v56
	v_mul_f32_e32 v129, 0xbfb8aa3b, v57
	v_mul_f32_e32 v130, 0xbfb8aa3b, v58
	v_mul_f32_e32 v131, 0xbfb8aa3b, v59
	v_exp_f32_e32 v128, v128
	v_exp_f32_e32 v129, v129
	v_exp_f32_e32 v130, v130
	v_exp_f32_e32 v131, v131
	v_add_f32_e32 v128, 1.0, v128
	v_add_f32_e32 v129, 1.0, v129
	v_add_f32_e32 v130, 1.0, v130
	v_add_f32_e32 v131, 1.0, v131
	v_rcp_f32_e32 v128, v128
	v_rcp_f32_e32 v130, v130
	v_rcp_f32_e32 v131, v131
	v_rcp_f32_e32 v129, v129
	v_lshl_add_u32 v153, v180, 11, v179
	v_cmp_lt_i32_e32 vcc, -1, v154
	v_pk_mul_f32 v[130:131], v[58:59], v[130:131]
	v_pk_mul_f32 v[128:129], v[56:57], v[128:129]
	v_pk_mul_f32 v[182:183], v[62:63], v[130:131]
	v_pk_mul_f32 v[156:157], v[60:61], v[128:129]
	v_pk_mul_f32 v[130:131], v[118:119], v[114:115]
	v_pk_mul_f32 v[128:129], v[116:117], v[112:113]
	v_cvt_pk_f16_f32 v185, v130, v131
	v_cvt_pk_f16_f32 v184, v128, v129
	v_cvt_pk_f16_f32 v183, v182, v183
	v_cvt_pk_f16_f32 v182, v156, v157
	global_store_dwordx2 v153, v[184:185], s[0:1] nt
	global_store_dwordx2 v153, v[182:183], s[38:39] nt
	s_and_saveexec_b64 s[4:5], vcc
	s_cbranch_execz .LBB0_247
	v_readlane_b32 s56, v255, 0
	v_cndmask_b32_e64 v156, v175, v176, s[86:87]
	v_mov_b32_e32 v157, v141
	v_readlane_b32 s62, v255, 6
	v_readlane_b32 s63, v255, 7
	v_ashrrev_i32_e32 v153, 31, v152
	v_mov_b32_e32 v155, v141
	v_lshl_add_u64 v[156:157], s[62:63], 0, v[156:157]
	v_lshlrev_b64 v[182:183], 13, v[152:153]
	v_lshl_add_u64 v[156:157], v[156:157], 0, v[182:183]
	v_lshlrev_b64 v[182:183], 12, v[154:155]
	v_lshl_add_u64 v[156:157], v[156:157], 0, v[182:183]
	v_lshl_add_u64 v[156:157], v[140:141], 2, v[156:157]
	v_readlane_b32 s57, v255, 1
	v_readlane_b32 s58, v255, 2
	v_readlane_b32 s59, v255, 3
	v_readlane_b32 s60, v255, 4
	v_readlane_b32 s61, v255, 5
	global_store_dwordx4 v[156:157], v[128:131], off nt

.LBB0_248:
	s_andn2_b64 vcc, exec, s[4:5]
	s_or_b32 s4, s16, s53
	s_cbranch_vccnz .LBB0_259
	v_lshl_or_b32 v153, v180, 10, s53
	v_cvt_pk_f16_f32 v131, v118, v119
	v_cvt_pk_f16_f32 v130, v116, v117
	v_cvt_pk_f16_f32 v129, v62, v63
	v_cvt_pk_f16_f32 v128, v60, v61
	s_and_b64 vcc, exec, s[10:11]
	s_mov_b64 s[16:17], -1
	s_cbranch_vccnz .LBB0_251
	v_or_b32_e32 v155, v153, v142
	v_lshlrev_b32_e32 v155, 1, v155
	v_or_b32_e32 v156, s4, v142
	s_mov_b64 s[16:17], 0
	global_store_dwordx4 v155, v[128:131], s[34:35] nt
.LBB0_251:
	s_andn2_b64 vcc, exec, s[16:17]
	s_cbranch_vccnz .LBB0_253
	v_readlane_b32 s16, v255, 42
	v_lshl_or_b32 v155, v180, 8, v160
	v_readlane_b32 s17, v255, 43
	v_mov_b32_e32 v156, v161
	s_nop 3
	global_store_dwordx4 v155, v[128:131], s[16:17] nt
.LBB0_253:
	s_movk_i32 s5, 0x4200
	v_cmp_eq_u32_e64 s[16:17], 1, v154
	v_cndmask_b32_e64 v130, v177, v178, s[86:87]
	v_mad_i64_i32 v[128:129], s[56:57], v152, s5, 0
	s_and_saveexec_b64 s[86:87], s[16:17]
	s_cbranch_execz .LBB0_255
	v_readlane_b32 s56, v255, 0
	v_lshlrev_b32_e32 v154, 2, v130
	v_mov_b32_e32 v155, v141
	v_readlane_b32 s62, v255, 6
	v_readlane_b32 s63, v255, 7
	v_ashrrev_i32_e32 v157, 31, v156
	v_readlane_b32 s57, v255, 1
	v_lshl_add_u64 v[154:155], s[62:63], 0, v[154:155]
	v_lshl_add_u64 v[154:155], v[154:155], 0, v[128:129]
	v_lshl_add_u64 v[154:155], v[156:157], 2, v[154:155]
	v_readlane_b32 s58, v255, 2
	v_readlane_b32 s59, v255, 3
	v_readlane_b32 s60, v255, 4
	v_readlane_b32 s61, v255, 5
	global_store_dwordx4 v[154:155], v[60:63], off nt
	global_store_dwordx4 v[154:155], v[116:119], off offset:16 nt
.LBB0_255:
	s_or_b64 exec, exec, s[86:87]
	s_and_b64 vcc, exec, s[10:11]
	s_cbranch_vccnz .LBB0_259
	v_or_b32_e32 v131, v153, v162
	v_cvt_pk_f16_f32 v157, v58, v59
	v_cvt_pk_f16_f32 v156, v56, v57
	v_cvt_pk_f16_f32 v155, v114, v115
	v_cvt_pk_f16_f32 v154, v112, v113
	v_lshlrev_b32_e32 v131, 1, v131
	global_store_dwordx4 v131, v[154:157], s[34:35] nt
	s_and_saveexec_b64 s[86:87], s[16:17]
	s_cbranch_execz .LBB0_258
	v_readlane_b32 s56, v255, 0
	v_lshlrev_b32_e32 v130, 2, v130
	v_mov_b32_e32 v131, v141
	v_readlane_b32 s62, v255, 6
	v_readlane_b32 s63, v255, 7
	s_ashr_i32 s5, s4, 31
	v_readlane_b32 s57, v255, 1
	v_lshl_add_u64 v[130:131], s[62:63], 0, v[130:131]
	v_lshl_add_u64 v[128:129], v[130:131], 0, v[128:129]
	v_lshl_add_u64 v[130:131], s[4:5], 0, v[142:143]
	v_lshl_add_u64 v[128:129], v[130:131], 2, v[128:129]
	v_readlane_b32 s58, v255, 2
	v_readlane_b32 s59, v255, 3
	v_readlane_b32 s60, v255, 4
	v_readlane_b32 s61, v255, 5
	global_store_dwordx4 v[128:129], v[112:115], off offset:512 nt
	global_store_dwordx4 v[128:129], v[56:59], off offset:528 nt

.LBB0_259:
	s_addk_i32 s55, 0x80
	v_or_b32_e32 v156, s55, v158
	s_and_b64 vcc, exec, s[14:15]
	s_mov_b64 s[16:17], -1
	s_cbranch_vccnz .LBB0_261
	v_mul_f32_e32 v128, 0xbfb8aa3b, v28
	v_mul_f32_e32 v129, 0xbfb8aa3b, v29
	v_mul_f32_e32 v130, 0xbfb8aa3b, v30
	v_mul_f32_e32 v131, 0xbfb8aa3b, v31
	v_exp_f32_e32 v128, v128
	v_exp_f32_e32 v129, v129
	v_exp_f32_e32 v130, v130
	v_exp_f32_e32 v131, v131
	v_add_f32_e32 v128, 1.0, v128
	v_add_f32_e32 v129, 1.0, v129
	v_add_f32_e32 v130, 1.0, v130
	v_add_f32_e32 v131, 1.0, v131
	v_rcp_f32_e32 v128, v128
	v_rcp_f32_e32 v130, v130
	v_rcp_f32_e32 v131, v131
	v_rcp_f32_e32 v129, v129
	v_pk_mul_f32 v[152:153], v[46:47], v[42:43]
	v_pk_mul_f32 v[154:155], v[44:45], v[40:41]
	v_pk_mul_f32 v[130:131], v[30:31], v[130:131]
	v_pk_mul_f32 v[128:129], v[28:29], v[128:129]
	v_pk_mul_f32 v[130:131], v[38:39], v[130:131]
	v_pk_mul_f32 v[128:129], v[36:37], v[128:129]
	v_lshl_add_u32 v157, v156, 11, v179
	v_cvt_pk_f16_f32 v153, v152, v153
	v_cvt_pk_f16_f32 v152, v154, v155
	v_cvt_pk_f16_f32 v131, v130, v131
	v_cvt_pk_f16_f32 v130, v128, v129
	s_mov_b64 s[16:17], 0
	global_store_dwordx2 v157, v[152:153], s[0:1] nt
	global_store_dwordx2 v157, v[130:131], s[38:39] nt
.LBB0_261:
	s_andn2_b64 vcc, exec, s[16:17]
	s_movk_i32 s86, 0x7fff
	s_cbranch_vccnz .LBB0_264
	v_lshlrev_b32_e32 v128, 10, v156
	s_and_b64 s[16:17], s[12:13], exec
	v_or3_b32 v128, v128, s53, v142
	s_cselect_b32 s16, 0x17e00000, s54
	v_lshl_or_b32 v129, v156, 8, v160
	v_lshlrev_b32_e32 v128, 1, v128
	s_cselect_b32 s5, 0, 0
	s_add_u32 s16, s76, s16
	v_cvt_pk_f16_f32 v155, v46, v47
	v_cvt_pk_f16_f32 v154, v44, v45
	v_cvt_pk_f16_f32 v153, v38, v39
	v_cvt_pk_f16_f32 v152, v36, v37
	v_cndmask_b32_e64 v129, v128, v129, s[12:13]
	s_addc_u32 s17, s77, s5
	s_and_b64 vcc, exec, s[10:11]
	global_store_dwordx4 v129, v[152:155], s[16:17] nt
	s_cbranch_vccnz .LBB0_264
	s_nop 0
	v_cvt_pk_f16_f32 v155, v30, v31
	v_cvt_pk_f16_f32 v154, v28, v29
	v_cvt_pk_f16_f32 v153, v42, v43
	v_cvt_pk_f16_f32 v152, v40, v41
	global_store_dwordx4 v128, v[152:155], s[34:35] offset:256 nt
.LBB0_264:
	v_or_b32_e32 v128, 1, v156
	s_and_b64 vcc, exec, s[14:15]
	s_mov_b64 s[16:17], -1
	s_cbranch_vccnz .LBB0_266
	v_mul_f32_e32 v129, 0xbfb8aa3b, v16
	v_exp_f32_e32 v129, v129
	v_mul_f32_e32 v130, 0xbfb8aa3b, v17
	v_mul_f32_e32 v131, 0xbfb8aa3b, v18
	v_exp_f32_e32 v152, v130
	v_add_f32_e32 v129, 1.0, v129
	v_rcp_f32_e32 v130, v129
	v_exp_f32_e32 v129, v131
	v_mul_f32_e32 v131, 0xbfb8aa3b, v19
	v_exp_f32_e32 v131, v131
	v_add_f32_e32 v154, 1.0, v152
	v_add_f32_e32 v129, 1.0, v129
	v_rcp_f32_e32 v152, v129
	v_add_f32_e32 v129, 1.0, v131
	v_rcp_f32_e32 v153, v129
	v_rcp_f32_e32 v131, v154
	v_pk_mul_f32 v[154:155], v[34:35], v[26:27]
	v_pk_mul_f32 v[180:181], v[32:33], v[24:25]
	v_pk_mul_f32 v[152:153], v[18:19], v[152:153]
	v_pk_mul_f32 v[130:131], v[16:17], v[130:131]
	v_pk_mul_f32 v[152:153], v[22:23], v[152:153]
	v_pk_mul_f32 v[130:131], v[20:21], v[130:131]
	v_lshl_add_u32 v129, v128, 11, v179
	v_cvt_pk_f16_f32 v155, v154, v155
	v_cvt_pk_f16_f32 v154, v180, v181
	v_cvt_pk_f16_f32 v153, v152, v153
	v_cvt_pk_f16_f32 v152, v130, v131
	s_mov_b64 s[16:17], 0
	global_store_dwordx2 v129, v[154:155], s[0:1] nt
	global_store_dwordx2 v129, v[152:153], s[38:39] nt
.LBB0_266:
	s_andn2_b64 vcc, exec, s[16:17]
	s_cbranch_vccnz .LBB0_269
	v_lshlrev_b32_e32 v129, 10, v128
	s_and_b64 s[16:17], s[12:13], exec
	v_lshl_or_b32 v130, v128, 8, v160
	v_or3_b32 v128, v129, s53, v142
	s_cselect_b32 s16, 0x17e00000, s54
	v_lshlrev_b32_e32 v128, 1, v128
	s_cselect_b32 s5, 0, 0
	s_add_u32 s16, s76, s16
	v_cvt_pk_f16_f32 v155, v34, v35
	v_cvt_pk_f16_f32 v154, v32, v33
	v_cvt_pk_f16_f32 v153, v22, v23
	v_cvt_pk_f16_f32 v152, v20, v21
	v_cndmask_b32_e64 v129, v128, v130, s[12:13]
	s_addc_u32 s17, s77, s5
	s_and_b64 vcc, exec, s[10:11]
	global_store_dwordx4 v129, v[152:155], s[16:17] nt
	s_cbranch_vccnz .LBB0_269
	s_nop 0
	v_cvt_pk_f16_f32 v155, v18, v19
	v_cvt_pk_f16_f32 v154, v16, v17
	v_cvt_pk_f16_f32 v153, v26, v27
	v_cvt_pk_f16_f32 v152, v24, v25
	global_store_dwordx4 v128, v[152:155], s[34:35] offset:256 nt

.LBB0_273:
	v_mul_f32_e32 v128, 0xbfb8aa3b, v0
	v_mul_f32_e32 v129, 0xbfb8aa3b, v1
	v_mul_f32_e32 v130, 0xbfb8aa3b, v2
	v_mul_f32_e32 v131, 0xbfb8aa3b, v3
	v_exp_f32_e32 v128, v128
	v_exp_f32_e32 v129, v129
	v_exp_f32_e32 v130, v130
	v_exp_f32_e32 v131, v131
	v_add_f32_e32 v128, 1.0, v128
	v_add_f32_e32 v129, 1.0, v129
	v_add_f32_e32 v130, 1.0, v130
	v_add_f32_e32 v131, 1.0, v131
	v_rcp_f32_e32 v128, v128
	v_rcp_f32_e32 v130, v130
	v_rcp_f32_e32 v131, v131
	v_rcp_f32_e32 v129, v129
	v_lshl_add_u32 v181, v180, 11, v179
	v_cmp_lt_i32_e32 vcc, -1, v153
	v_pk_mul_f32 v[130:131], v[2:3], v[130:131]
	v_pk_mul_f32 v[128:129], v[0:1], v[128:129]
	v_pk_mul_f32 v[184:185], v[6:7], v[130:131]
	v_pk_mul_f32 v[182:183], v[4:5], v[128:129]
	v_pk_mul_f32 v[130:131], v[110:111], v[106:107]
	v_pk_mul_f32 v[128:129], v[108:109], v[104:105]
	v_cvt_pk_f16_f32 v187, v130, v131
	v_cvt_pk_f16_f32 v186, v128, v129
	v_cvt_pk_f16_f32 v185, v184, v185
	v_cvt_pk_f16_f32 v184, v182, v183
	global_store_dwordx2 v181, v[186:187], s[0:1] nt
	global_store_dwordx2 v181, v[184:185], s[38:39] nt
	s_and_saveexec_b64 s[16:17], vcc
	s_cbranch_execz .LBB0_275
	v_readlane_b32 s56, v255, 0
	v_readlane_b32 s62, v255, 6
	v_readlane_b32 s63, v255, 7
	v_ashrrev_i32_e32 v153, 31, v152
	v_lshlrev_b64 v[152:153], 13, v[152:153]
	v_lshl_add_u64 v[154:155], v[154:155], 2, s[62:63]
	v_lshl_add_u64 v[152:153], v[154:155], 0, v[152:153]
	v_lshl_add_u64 v[152:153], v[140:141], 2, v[152:153]
	v_readlane_b32 s57, v255, 1
	v_readlane_b32 s58, v255, 2
	v_readlane_b32 s59, v255, 3
	v_readlane_b32 s60, v255, 4
	v_readlane_b32 s61, v255, 5
	global_store_dwordx4 v[152:153], v[128:131], off nt

.LBB0_279:
	v_lshlrev_b32_e32 v128, 10, v180
	v_or3_b32 v128, v128, s53, v142
	v_lshl_or_b32 v129, v180, 8, v160
	v_lshlrev_b32_e32 v128, 1, v128
	v_cndmask_b32_e64 v129, v128, v129, s[12:13]
	s_and_b64 s[12:13], s[12:13], exec
	s_cselect_b32 s12, 0x17e00000, s54
	s_cselect_b32 s13, 0, 0
	s_add_u32 s12, s76, s12
	v_cvt_pk_f16_f32 v155, v110, v111
	v_cvt_pk_f16_f32 v154, v108, v109
	v_cvt_pk_f16_f32 v153, v6, v7
	v_cvt_pk_f16_f32 v152, v4, v5
	s_addc_u32 s13, s77, s13
	s_and_b64 vcc, exec, s[10:11]
	global_store_dwordx4 v129, v[152:155], s[12:13] nt
	s_cbranch_vccnz .LBB0_281
	s_nop 0
	v_cvt_pk_f16_f32 v155, v2, v3
	v_cvt_pk_f16_f32 v154, v0, v1
	v_cvt_pk_f16_f32 v153, v106, v107
	v_cvt_pk_f16_f32 v152, v104, v105
	global_store_dwordx4 v128, v[152:155], s[34:35] offset:256 nt

.LBB0_285:
	v_mul_f32_e32 v128, 0xbfb8aa3b, v8
	v_mul_f32_e32 v129, 0xbfb8aa3b, v9
	v_mul_f32_e32 v130, 0xbfb8aa3b, v10
	v_mul_f32_e32 v131, 0xbfb8aa3b, v11
	v_exp_f32_e32 v128, v128
	v_exp_f32_e32 v129, v129
	v_exp_f32_e32 v130, v130
	v_exp_f32_e32 v131, v131
	v_add_f32_e32 v128, 1.0, v128
	v_add_f32_e32 v129, 1.0, v129
	v_add_f32_e32 v130, 1.0, v130
	v_add_f32_e32 v131, 1.0, v131
	v_rcp_f32_e32 v128, v128
	v_rcp_f32_e32 v130, v130
	v_rcp_f32_e32 v131, v131
	v_rcp_f32_e32 v129, v129
	v_lshl_add_u32 v153, v180, 11, v179
	v_cmp_lt_i32_e32 vcc, -1, v154
	v_pk_mul_f32 v[130:131], v[10:11], v[130:131]
	v_pk_mul_f32 v[128:129], v[8:9], v[128:129]
	v_pk_mul_f32 v[182:183], v[14:15], v[130:131]
	v_pk_mul_f32 v[156:157], v[12:13], v[128:129]
	v_pk_mul_f32 v[130:131], v[102:103], v[98:99]
	v_pk_mul_f32 v[128:129], v[100:101], v[96:97]
	v_cvt_pk_f16_f32 v185, v130, v131
	v_cvt_pk_f16_f32 v184, v128, v129
	v_cvt_pk_f16_f32 v183, v182, v183
	v_cvt_pk_f16_f32 v182, v156, v157
	global_store_dwordx2 v153, v[184:185], s[0:1] nt
	global_store_dwordx2 v153, v[182:183], s[38:39] nt
	s_and_saveexec_b64 s[0:1], vcc
	s_cbranch_execz .LBB0_287
	v_readlane_b32 s56, v255, 0
	v_cndmask_b32_e64 v156, v175, v176, s[16:17]
	v_mov_b32_e32 v157, v141
	v_readlane_b32 s62, v255, 6
	v_readlane_b32 s63, v255, 7
	v_ashrrev_i32_e32 v153, 31, v152
	v_mov_b32_e32 v155, v141
	v_lshl_add_u64 v[156:157], s[62:63], 0, v[156:157]
	v_lshlrev_b64 v[182:183], 13, v[152:153]
	v_lshl_add_u64 v[156:157], v[156:157], 0, v[182:183]
	v_lshlrev_b64 v[182:183], 12, v[154:155]
	v_lshl_add_u64 v[156:157], v[156:157], 0, v[182:183]
	v_lshl_add_u64 v[156:157], v[140:141], 2, v[156:157]
	v_readlane_b32 s57, v255, 1
	v_readlane_b32 s58, v255, 2
	v_readlane_b32 s59, v255, 3
	v_readlane_b32 s60, v255, 4
	v_readlane_b32 s61, v255, 5
	global_store_dwordx4 v[156:157], v[128:131], off nt

.LBB0_291:
	v_lshl_or_b32 v153, v180, 10, s53
	v_cvt_pk_f16_f32 v131, v102, v103
	v_cvt_pk_f16_f32 v130, v100, v101
	v_cvt_pk_f16_f32 v129, v14, v15
	v_cvt_pk_f16_f32 v128, v12, v13
	s_and_b64 vcc, exec, s[10:11]
	s_mov_b64 s[0:1], -1
	s_cbranch_vccnz .LBB0_293
	v_or_b32_e32 v140, v153, v142
	v_lshlrev_b32_e32 v140, 1, v140
	v_or_b32_e32 v156, s4, v142
	s_mov_b64 s[0:1], 0
	global_store_dwordx4 v140, v[128:131], s[34:35] nt
.LBB0_293:
	s_andn2_b64 vcc, exec, s[0:1]
	s_cbranch_vccnz .LBB0_295
	v_readlane_b32 s0, v255, 42
	v_lshl_or_b32 v140, v180, 8, v160
	v_readlane_b32 s1, v255, 43
	v_mov_b32_e32 v156, v161
	s_nop 3
	global_store_dwordx4 v140, v[128:131], s[0:1] nt
.LBB0_295:
	s_movk_i32 s0, 0x4200
	v_cmp_eq_u32_e64 s[12:13], 1, v154
	v_cndmask_b32_e64 v130, v177, v178, s[16:17]
	v_mad_i64_i32 v[128:129], s[0:1], v152, s0, 0
	s_and_saveexec_b64 s[0:1], s[12:13]
	s_cbranch_execz .LBB0_297
	v_readlane_b32 s56, v255, 0
	v_lshlrev_b32_e32 v140, 2, v130
	v_readlane_b32 s62, v255, 6
	v_readlane_b32 s63, v255, 7
	v_ashrrev_i32_e32 v157, 31, v156
	v_readlane_b32 s57, v255, 1
	v_lshl_add_u64 v[154:155], s[62:63], 0, v[140:141]
	v_lshl_add_u64 v[154:155], v[154:155], 0, v[128:129]
	v_lshl_add_u64 v[154:155], v[156:157], 2, v[154:155]
	v_readlane_b32 s58, v255, 2
	v_readlane_b32 s59, v255, 3
	v_readlane_b32 s60, v255, 4
	v_readlane_b32 s61, v255, 5
	global_store_dwordx4 v[154:155], v[12:15], off nt
	global_store_dwordx4 v[154:155], v[100:103], off offset:16 nt
.LBB0_297:
	s_or_b64 exec, exec, s[0:1]
	s_and_b64 vcc, exec, s[10:11]
	s_cbranch_vccnz .LBB0_301
	v_or_b32_e32 v131, v153, v162
	v_cvt_pk_f16_f32 v157, v10, v11
	v_cvt_pk_f16_f32 v156, v8, v9
	v_cvt_pk_f16_f32 v155, v98, v99
	v_cvt_pk_f16_f32 v154, v96, v97
	v_lshlrev_b32_e32 v131, 1, v131
	global_store_dwordx4 v131, v[154:157], s[34:35] nt
	s_and_saveexec_b64 s[0:1], s[12:13]
	s_cbranch_execz .LBB0_300
	v_readlane_b32 s56, v255, 0
	v_lshlrev_b32_e32 v140, 2, v130
	v_readlane_b32 s62, v255, 6
	v_readlane_b32 s63, v255, 7
	s_ashr_i32 s5, s4, 31
	v_readlane_b32 s57, v255, 1
	v_lshl_add_u64 v[130:131], s[62:63], 0, v[140:141]
	v_lshl_add_u64 v[128:129], v[130:131], 0, v[128:129]
	v_lshl_add_u64 v[130:131], s[4:5], 0, v[142:143]
	v_lshl_add_u64 v[128:129], v[130:131], 2, v[128:129]
	v_readlane_b32 s58, v255, 2
	v_readlane_b32 s59, v255, 3
	v_readlane_b32 s60, v255, 4
	v_readlane_b32 s61, v255, 5
	global_store_dwordx4 v[128:129], v[96:99], off offset:512 nt
	global_store_dwordx4 v[128:129], v[8:11], off offset:528 nt
